# grid barrier: non-leader workgroups poll the top-level generation word directly (flat release), skipping the per-XCD generation hop
# baseline (speedup 1.0000x reference)
.LBB0_881:
	s_or_b64 exec, exec, s[2:3]
	v_cvt_f32_u32_e32 v9, v7
	s_waitcnt vmcnt(0)
	v_readfirstlane_b32 s2, v8
	v_sub_u32_e32 v8, 0, v7
	v_rcp_iflag_f32_e32 v9, v9
	v_add_u32_e32 v10, s2, v1
	v_mul_f32_e32 v9, 0x4f7ffffe, v9
	v_cvt_u32_f32_e32 v9, v9
	v_mul_lo_u32 v1, v8, v9
	v_mul_hi_u32 v1, v9, v1
	v_add_u32_e32 v1, v9, v1
	v_mul_hi_u32 v1, v10, v1
	v_mul_lo_u32 v8, v1, v7
	v_sub_u32_e32 v8, v10, v8
	v_add_u32_e32 v9, 1, v1
	v_cmp_ge_u32_e32 vcc, v8, v7
	s_nop 1
	v_cndmask_b32_e32 v1, v1, v9, vcc
	v_sub_u32_e32 v9, v8, v7
	v_cndmask_b32_e32 v8, v8, v9, vcc
	v_add_u32_e32 v9, 1, v1
	v_cmp_ge_u32_e32 vcc, v8, v7
	v_add_u32_e32 v8, 1, v10
	s_nop 0
	v_cndmask_b32_e32 v1, v1, v9, vcc
	v_mul_lo_u32 v9, v7, v1
	v_add_u32_e32 v7, v9, v7
	v_cmp_ne_u32_e32 vcc, v8, v7
	s_and_saveexec_b64 s[2:3], vcc
	s_xor_b64 s[2:3], exec, s[2:3]
	s_cbranch_execz .LBB0_895
	v_readlane_b32 s4, v251, 41
	v_readlane_b32 s5, v251, 42
	s_waitcnt lgkmcnt(0)
	s_nop 3
	global_load_dword v6, v139, s[4:5] sc1
	s_waitcnt vmcnt(0)
	v_cmp_eq_u32_e32 vcc, v6, v1
	s_and_saveexec_b64 s[22:23], vcc
	s_cbranch_execz .LBB0_894
	s_mov_b32 s4, 1
	s_mov_b64 s[24:25], 0
	s_branch .LBB0_885
